# M1: next round's gate inputs prefetched at the end of the previous round (and before the loop) so the two gate waves no longer start their q loads a memory round trip late
# speedup vs baseline: 1.0033x; 1.0033x over previous
; __device__ __forceinline__ void m1_phase(const Params& p, unsigned char* ldsg, int G) {
;     const int tid = threadIdx.x, lane = tid & 63, wave = __builtin_amdgcn_readfirstlane(tid >> 6), fr = lane & 15, fq = lane >> 4;
;     const int half = wave >> 2, hw = wave & 3, htid = tid & 255;
;     unsigned char* ws = p.ws;
;     const bf16* PROJ = (const bf16*)(ws + WS_HB); const float* GATES = (const float*)(ws + WS_GATES);
;     bf16* DCB = (bf16*)p.out; bf16* QKC = (bf16*)((unsigned char*)p.out + 32 * MiB); float* DN = (float*)(ws + WS_DN); float* GARR = (float*)(ws + WS_SC); float* AMAXARR = GARR + 1024;
;     bf16* KT = (bf16*)(ldsg + half * 40960); bf16* VT = KT + 128 * TP; float* sW = (float*)(ldsg + half * 40960 + 36864);
;     for (int r = blockIdx.x; r < NCH * NH / 2; r += G) {
;         const int c = r >> 1, h = 2 * (r & 1) + half, u = c * 4 + h, t0 = c * CL;
;         if (hw == 0) {
;             const float ig = GATES[(size_t)(t0 + lane) * 8 + h], fp = GATES[(size_t)(t0 + lane) * 8 + 4 + h];
.LBB0_608:
	s_or_b64 exec, exec, s[0:1]
	s_add_u32 s56, s70, 0x2000000
	s_addc_u32 s57, s71, 0
	s_add_u32 s34, s72, 0x500000
	s_addc_u32 s35, s73, 0
	s_add_u32 s36, s72, 0x501000
	v_lshrrev_b32_e32 v159, 4, v153
	s_addc_u32 s37, s73, 0
	v_readfirstlane_b32 s0, v240
	s_cmpk_gt_i32 s86, 0x1ff
	v_cmp_gt_u32_e64 s[8:9], 2, v153
	v_cmp_gt_u32_e64 s[10:11], 4, v153
	v_cmp_gt_u32_e64 s[12:13], 8, v153
	v_cmp_gt_u32_e64 s[14:15], 32, v153
	v_lshlrev_b32_e32 v92, 3, v159
	v_lshlrev_b32_e32 v167, 8, v152
	v_and_b32_e32 v157, 8, v152
	s_waitcnt lgkmcnt(0)
	s_barrier
	s_cbranch_scc1 .LBB0_648
	s_ashr_i32 s2, s0, 2
	v_and_b32_e32 v64, 0x78, v230
	s_mul_i32 s1, s2, 0xa000
	v_mov_b32_e32 v67, 0
	v_lshlrev_b32_e32 v66, 1, v64
	v_and_b32_e32 v0, 56, v230
	s_add_i32 s1, s1, 0
	v_and_b32_e32 v2, 0xff, v152
	v_lshl_add_u64 v[68:69], s[56:57], 0, v[66:67]
	v_bitop3_b32 v0, v175, v0, 60 bitop3:0x6c
	v_and_b32_e32 v66, 0x100, v167
	s_and_b32 s3, s0, 3
	v_and_b32_e32 v118, 60, v175
	v_lshl_add_u32 v4, v0, 1, s1
	v_lshl_add_u64 v[0:1], s[70:71], 0, v[66:67]
	v_mov_b32_e32 v93, v67
	s_movk_i32 s0, 0x80
	v_lshlrev_b32_e32 v66, 2, v2
	v_mov_b32_e32 v3, s1
	v_lshl_add_u32 v65, v153, 2, s1
	v_lshl_add_u32 v120, v118, 2, s1
	v_lshl_or_b32 v5, s3, 5, v234
	v_lshl_add_u64 v[70:71], v[0:1], 0, v[92:93]
	v_cmp_gt_u32_e64 s[20:21], s0, v2
	s_movk_i32 s6, 0x90
	v_lshl_add_u64 v[0:1], s[72:73], 0, v[66:67]
	s_mov_b64 s[0:1], 0x480000
	v_mad_u32_u24 v93, v2, s6, v3
	v_lshl_add_u64 v[72:73], v[0:1], 0, s[0:1]
	v_mad_u32_u24 v1, v5, s6, v3
	v_bitop3_b32 v2, v5, v92, 40 bitop3:0x6c
	v_lshl_add_u32 v121, v2, 1, v1
	v_or_b32_e32 v2, 32, v92
	v_bitop3_b32 v7, v5, v2, 40 bitop3:0x6c
	v_or_b32_e32 v5, 16, v5
	v_lshl_add_u32 v122, v7, 1, v1
	v_add_u32_e32 v1, 0x900, v1
	v_bitop3_b32 v7, v5, v92, 56 bitop3:0x6c
	v_bitop3_b32 v2, v5, v2, 56 bitop3:0x6c
	v_lshl_add_u32 v123, v7, 1, v1
	v_lshl_add_u32 v124, v2, 1, v1
	v_mad_u32_u24 v1, v234, s6, v3
	v_bitop3_b32 v2, v92, v152, 8 bitop3:0x78
	v_lshlrev_b32_e32 v6, 7, v152
	v_lshl_add_u32 v125, v2, 1, v1
	v_bitop3_b32 v2, v92, v157, 32 bitop3:0x36
	v_lshl_add_u32 v126, v2, 1, v1
	v_and_b32_e32 v2, 0x700, v6
	v_lshl_or_b32 v127, s3, 12, v2
	v_or_b32_e32 v2, 16, v234
	v_bitop3_b32 v3, v234, 24, 16 bitop3:0xc8
	v_bitop3_b32 v2, v92, v2, 24 bitop3:0x78
	v_bitop3_b32 v3, v92, v3, 32 bitop3:0x36
	v_add_u32_e32 v5, 0x900, v1
	v_lshlrev_b32_e32 v2, 1, v2
	v_lshlrev_b32_e32 v3, 1, v3
	v_add_u32_e32 v129, v5, v2
	v_add_u32_e32 v130, v5, v3
	v_or_b32_e32 v5, 32, v234
	v_bitop3_b32 v6, v234, 40, 32 bitop3:0xc8
	v_bitop3_b32 v5, v92, v5, 40 bitop3:0x78
	v_bitop3_b32 v6, v92, v6, 32 bitop3:0x36
	v_add_u32_e32 v7, 0x1200, v1
	v_lshlrev_b32_e32 v5, 1, v5
	v_lshlrev_b32_e32 v6, 1, v6
	v_add_u32_e32 v131, v7, v5
	v_add_u32_e32 v132, v7, v6
	v_or_b32_e32 v7, 48, v234
	v_bitop3_b32 v8, v234, 56, 48 bitop3:0xc8
	v_bitop3_b32 v7, v92, v7, 56 bitop3:0x78
	v_bitop3_b32 v8, v92, v8, 32 bitop3:0x36
	v_mul_u32_u24_e32 v0, 0x90, v64
	v_add_u32_e32 v9, 0x1b00, v1
	v_lshlrev_b32_e32 v7, 1, v7
	v_lshlrev_b32_e32 v8, 1, v8
	v_add_u32_e32 v133, v9, v7
	v_add_u32_e32 v134, v9, v8
	v_add_u32_e32 v9, 0x2d00, v1
	v_add_u32_e32 v142, v4, v0
	v_mbcnt_lo_u32_b32 v0, -1, 0
	s_cmp_eq_u32 s3, 0
	v_add_u32_e32 v135, v9, v2
	v_add_u32_e32 v2, 0x3600, v1
	v_add_u32_e32 v1, 0x3f00, v1
	v_mbcnt_hi_u32_b32 v144, -1, v0
	v_bfrev_b32_e32 v0, 0.5
	s_cselect_b64 s[4:5], -1, 0
	v_cmp_eq_u32_e64 s[16:17], 0, v153
	v_cmp_gt_u32_e64 s[18:19], 16, v153
	v_or_b32_e32 v119, 0x200, v64
	v_or_b32_e32 v128, 0x800, v127
	v_add_u32_e32 v136, v9, v3
	v_add_u32_e32 v137, v2, v5
	v_add_u32_e32 v138, v2, v6
	v_add_u32_e32 v139, v1, v7
	v_add_u32_e32 v140, v1, v8
	s_mov_b32 s3, 0xbfb8aa3b
	v_mov_b32_e32 v141, 0x3ecc95a3
	s_mov_b32 s33, 0x3f317218
	s_mov_b32 s43, 0x33800000
	s_mov_b32 s46, 0x3fb8aa3b
	s_mov_b32 s47, 0xc2ce8ed0
	s_mov_b32 s62, 0x42b17218
	s_movk_i32 s63, 0x1600
	s_mov_b32 s64, 0xffff0000
	s_mov_b64 s[6:7], 0x1000
	s_mov_b64 s[38:39], 0x2000
	s_movk_i32 s65, 0x2000
	s_mov_b64 s[40:41], 0x3000
	s_movk_i32 s80, 0x3000
	s_movk_i32 s81, 0x7fff
	s_mov_b32 s42, 0x3db504f3
	v_lshlrev_b32_e32 v66, 1, v64
	v_mov_b32_e32 v143, 0x7f800000
	v_lshl_or_b32 v145, v144, 2, v0
	v_mov_b32_e32 v146, 1
	s_mov_b32 s82, s86
	s_andn2_b64 vcc, exec, s[4:5]
	s_cbranch_vccnz .Lm1pf_skip_0
	s_lshl_b32 s0, s82, 1
	s_ashr_i32 s83, s82, 1
	s_and_b32 s0, s0, 2
	s_add_i32 s44, s0, s2
	s_lshl_b32 s22, s83, 6
	v_or_b32_e32 v218, s22, v153
	v_ashrrev_i32_e32 v219, 31, v218
	v_lshlrev_b64 v[218:219], 5, v[218:219]
	s_ashr_i32 s45, s44, 31
	v_lshl_add_u64 v[218:219], s[54:55], 0, v[218:219]
	v_lshl_add_u64 v[218:219], s[44:45], 2, v[218:219]
	global_load_dword v216, v[218:219], off offset:16
	global_load_dword v217, v[218:219], off

; __device__ __forceinline__ float log_sigmoid_f(float x) { return fminf(x, 0.f) - log1pf(expf(-fabsf(x))); }
; __device__ __forceinline__ void m1_phase(const Params& p, unsigned char* ldsg, int G) {
;     ...
;     for (int r = blockIdx.x; r < NCH * NH / 2; r += G) {
;         const int c = r >> 1, h = 2 * (r & 1) + half, u = c * 4 + h, t0 = c * CL;
;         if (hw == 0) {
;             const float ig = GATES[(size_t)(t0 + lane) * 8 + h], fp = GATES[(size_t)(t0 + lane) * 8 + 4 + h];
;             const float b = wave_incl_sum(log_sigmoid_f(fp), lane);
;             const float g = __shfl(b, 63);
;             const float a = g - b + ig;
;             const float amax = wave_max(a);
;             sW[lane] = expf(a - amax);
;             if (lane == 0) { GARR[h * NCH + c] = g; AMAXARR[h * NCH + c] = amax; }
;         }
.LBB0_610:
	s_or_b64 exec, exec, s[0:1]
	s_add_i32 s82, s82, s74
	s_cmpk_gt_i32 s82, 0x1ff
	s_cbranch_scc1 .Lm1pf_skip_1
	s_andn2_b64 vcc, exec, s[4:5]
	s_cbranch_vccnz .Lm1pf_skip_1
	s_lshl_b32 s0, s82, 1
	s_ashr_i32 s83, s82, 1
	s_and_b32 s0, s0, 2
	s_add_i32 s44, s0, s2
	s_lshl_b32 s22, s83, 6
	v_or_b32_e32 v218, s22, v153
	v_ashrrev_i32_e32 v219, 31, v218
	v_lshlrev_b64 v[218:219], 5, v[218:219]
	s_ashr_i32 s45, s44, 31
	v_lshl_add_u64 v[218:219], s[54:55], 0, v[218:219]
	v_lshl_add_u64 v[218:219], s[44:45], 2, v[218:219]
	global_load_dword v216, v[218:219], off offset:16
	global_load_dword v217, v[218:219], off
.Lm1pf_skip_1:
	s_cmpk_gt_i32 s82, 0x1ff
	s_barrier
	s_cbranch_scc1 .LBB0_648
.LBB0_611:
	s_lshl_b32 s0, s82, 1
	s_ashr_i32 s83, s82, 1
	s_and_b32 s0, s0, 2
	s_add_i32 s44, s0, s2
	s_andn2_b64 vcc, exec, s[4:5]
	s_lshl_b32 s22, s83, 6
	s_cbranch_vccnz .LBB0_615
	s_ashr_i32 s45, s44, 31
	s_waitcnt vmcnt(0)
	v_mov_b32_e32 v2, v216
	v_mov_b32_e32 v5, v217
	s_mov_b32 s0, 0xb2a5705f
	v_and_b32_e32 v3, 64, v144
	v_add_u32_e32 v4, -1, v144
	s_mov_b32 s1, 0x42ce8ed0
	v_cmp_lt_i32_e32 vcc, v4, v3
	s_mov_b32 s23, 0xc2b17218
	s_mov_b32 s24, 0x3f2aaaab
	v_cndmask_b32_e32 v4, v4, v144, vcc
	s_mov_b32 s25, 0x7f800000
	v_lshlrev_b32_e32 v4, 2, v4
	s_waitcnt vmcnt(1)
	v_mul_f32_e64 v0, |v2|, s3
	v_fma_f32 v1, |v2|, s3, -v0
	v_rndne_f32_e32 v6, v0
	v_fma_f32 v1, |v2|, s0, v1
	v_sub_f32_e32 v0, v0, v6
	v_add_f32_e32 v0, v0, v1
	v_cvt_i32_f32_e32 v6, v6
	v_exp_f32_e32 v0, v0
	v_cmp_ngt_f32_e64 vcc, |v2|, s1
	v_max_f32_e32 v1, v2, v2
	v_min_f32_e32 v7, 0, v1
	v_ldexp_f32 v0, v0, v6
	v_cndmask_b32_e32 v0, 0, v0, vcc
	v_cmp_nlt_f32_e64 vcc, |v2|, s23
	s_nop 1
	v_cndmask_b32_e32 v2, v143, v0, vcc
	v_add_f32_e32 v6, 1.0, v2
	v_add_f32_e32 v8, -1.0, v6
	v_frexp_mant_f32_e32 v9, v6
	v_cvt_f64_f32_e32 v[0:1], v6
	v_sub_f32_e32 v10, v8, v6
	v_frexp_exp_i32_f64_e32 v0, v[0:1]
	v_cmp_gt_f32_e32 vcc, s24, v9
	v_sub_f32_e32 v8, v2, v8
	v_add_f32_e32 v1, 1.0, v10
	v_subbrev_co_u32_e32 v0, vcc, 0, v0, vcc
	v_add_f32_e32 v1, v8, v1
	v_sub_u32_e32 v8, 0, v0
	v_cvt_f32_i32_e32 v0, v0
	v_ldexp_f32 v6, v6, v8
	v_ldexp_f32 v1, v1, v8
	v_add_f32_e32 v8, -1.0, v6
	v_add_f32_e32 v9, 1.0, v6
	v_add_f32_e32 v10, 1.0, v8
	v_add_f32_e32 v11, -1.0, v9
	v_sub_f32_e32 v10, v6, v10
	v_sub_f32_e32 v6, v6, v11
	v_mul_f32_e32 v11, 0x3f317218, v0
	v_add_f32_e32 v10, v1, v10
	v_add_f32_e32 v1, v1, v6
	v_fma_f32 v6, v0, s33, -v11
	v_add_f32_e32 v12, v8, v10
	v_add_f32_e32 v13, v9, v1
	v_fmac_f32_e32 v6, 0xb102e308, v0
	v_sub_f32_e32 v0, v8, v12
	v_sub_f32_e32 v8, v9, v13
	v_rcp_f32_e32 v9, v13
	v_add_f32_e32 v14, v11, v6
	v_add_f32_e32 v1, v1, v8
	v_sub_f32_e32 v8, v14, v11
	v_sub_f32_e32 v6, v6, v8
	v_mul_f32_e32 v8, v12, v9
	v_add_f32_e32 v0, v10, v0
	v_mul_f32_e32 v10, v13, v8
	v_fma_f32 v11, v8, v13, -v10
	v_fmac_f32_e32 v11, v8, v1
	v_add_f32_e32 v15, v10, v11
	v_sub_f32_e32 v16, v12, v15
	v_sub_f32_e32 v10, v15, v10
	v_sub_f32_e32 v12, v12, v16
	v_sub_f32_e32 v10, v10, v11
	v_sub_f32_e32 v11, v12, v15
	v_add_f32_e32 v0, v0, v11
	v_add_f32_e32 v0, v10, v0
	v_add_f32_e32 v10, v16, v0
	v_mul_f32_e32 v11, v9, v10
	v_sub_f32_e32 v12, v16, v10
	v_mul_f32_e32 v15, v13, v11
	v_add_f32_e32 v0, v0, v12
	v_add_f32_e32 v12, v8, v11
	v_fma_f32 v13, v11, v13, -v15
	v_sub_f32_e32 v8, v12, v8
	v_fmac_f32_e32 v13, v11, v1
	v_sub_f32_e32 v1, v11, v8
	v_add_f32_e32 v8, v15, v13
	v_sub_f32_e32 v11, v8, v15
	v_sub_f32_e32 v15, v10, v8
	v_sub_f32_e32 v10, v10, v15
	v_sub_f32_e32 v8, v10, v8
	v_sub_f32_e32 v11, v11, v13
	v_add_f32_e32 v0, v0, v8
	v_add_f32_e32 v0, v11, v0
	v_add_f32_e32 v0, v15, v0
	v_mul_f32_e32 v0, v9, v0
	v_add_f32_e32 v0, v1, v0
	v_add_f32_e32 v1, v12, v0
	v_mul_f32_e32 v8, v1, v1
	v_fmamk_f32 v11, v8, 0x3e9b6dac, v141
	v_sub_f32_e32 v9, v1, v12
	v_ldexp_f32 v10, v1, 1
	v_mul_f32_e32 v1, v1, v8
	v_fmaak_f32 v8, v8, v11, 0x3f2aaada
	v_mul_f32_e32 v1, v1, v8
	v_add_f32_e32 v8, v10, v1
	v_sub_f32_e32 v0, v0, v9
	v_sub_f32_e32 v9, v8, v10
	v_ldexp_f32 v0, v0, 1
	v_sub_f32_e32 v1, v1, v9
	v_add_f32_e32 v0, v0, v1
	v_add_f32_e32 v1, v8, v0
	v_sub_f32_e32 v8, v1, v8
	v_add_f32_e32 v9, v14, v1
	v_sub_f32_e32 v0, v0, v8
	v_sub_f32_e32 v8, v9, v14
	v_sub_f32_e32 v10, v9, v8
	v_sub_f32_e32 v1, v1, v8
	v_add_f32_e32 v8, v6, v0
	v_sub_f32_e32 v10, v14, v10
	v_sub_f32_e32 v11, v8, v6
	v_add_f32_e32 v1, v1, v10
	v_sub_f32_e32 v10, v8, v11
	v_sub_f32_e32 v0, v0, v11
	v_sub_f32_e32 v6, v6, v10
	v_add_f32_e32 v1, v8, v1
	v_add_f32_e32 v0, v0, v6
	v_add_f32_e32 v6, v9, v1
	v_sub_f32_e32 v8, v6, v9
	v_sub_f32_e32 v1, v1, v8
	v_add_f32_e32 v0, v0, v1
	v_add_f32_e32 v0, v6, v0
	v_cmp_neq_f32_e32 vcc, s25, v2
	s_nop 1
	v_cndmask_b32_e32 v0, v143, v0, vcc
	v_cmp_lt_f32_e64 vcc, |v2|, s43
	s_nop 1
	v_cndmask_b32_e32 v0, v0, v2, vcc
	v_sub_f32_e32 v0, v7, v0
	s_nop 1
	v_add_f32_dpp v0, v0, v0 row_shr:1 row_mask:0xf bank_mask:0xf bound_ctrl:0
	s_nop 1
	v_add_f32_dpp v0, v0, v0 row_shr:2 row_mask:0xf bank_mask:0xf bound_ctrl:0
	s_nop 1
	v_add_f32_dpp v0, v0, v0 row_shr:4 row_mask:0xf bank_mask:0xf bound_ctrl:0
	s_nop 1
	v_add_f32_dpp v0, v0, v0 row_shr:8 row_mask:0xf bank_mask:0xf bound_ctrl:0
	s_nop 1
	v_add_f32_dpp v0, v0, v0 row_bcast:15 row_mask:0xa bank_mask:0xf
	s_nop 1
	v_add_f32_dpp v0, v0, v0 row_bcast:31 row_mask:0xc bank_mask:0xf
	s_nop 1
	v_readlane_b32 s98, v0, 63
	s_waitcnt vmcnt(0)
	s_nop 1
	v_sub_f32_e32 v1, s98, v0
	v_add_f32_e32 v4, v5, v1
	v_mov_b32_e32 v1, v4
	s_nop 1
	v_max_f32_dpp v1, v1, v1 row_shr:1 row_mask:0xf bank_mask:0xf
	s_nop 1
	v_max_f32_dpp v1, v1, v1 row_shr:2 row_mask:0xf bank_mask:0xf
	s_nop 1
	v_max_f32_dpp v1, v1, v1 row_shr:4 row_mask:0xf bank_mask:0xf
	s_nop 1
	v_max_f32_dpp v1, v1, v1 row_shr:8 row_mask:0xf bank_mask:0xf
	s_nop 1
	v_max_f32_dpp v1, v1, v1 row_bcast:15 row_mask:0xa bank_mask:0xf
	s_nop 1
	v_max_f32_dpp v1, v1, v1 row_bcast:31 row_mask:0xc bank_mask:0xf
	s_nop 1
	v_readlane_b32 s99, v1, 63
	s_nop 2
	v_mov_b32_e32 v1, s99
	v_mov_b32_e32 v0, s98
	v_sub_f32_e32 v2, v4, v1
	v_mul_f32_e32 v3, 0x3fb8aa3b, v2
	v_fma_f32 v4, v2, s46, -v3
	v_rndne_f32_e32 v5, v3
	v_fmac_f32_e32 v4, 0x32a5705f, v2
	v_sub_f32_e32 v3, v3, v5
	v_add_f32_e32 v3, v3, v4
	v_cvt_i32_f32_e32 v5, v5
	v_exp_f32_e32 v3, v3
	v_cmp_ngt_f32_e32 vcc, s47, v2
	v_ldexp_f32 v3, v3, v5
	s_nop 0
	v_cndmask_b32_e32 v3, 0, v3, vcc
	v_cmp_nlt_f32_e32 vcc, s62, v2
	s_nop 1
	v_cndmask_b32_e32 v2, v143, v3, vcc
	ds_write_b32 v65, v2 offset:36864
	s_and_saveexec_b64 s[0:1], s[16:17]
	s_cbranch_execz .LBB0_614
	s_lshl_b32 s23, s44, 8
	s_add_i32 s24, s23, s83
	s_ashr_i32 s25, s24, 31
	s_lshl_b64 s[24:25], s[24:25], 2
	s_add_u32 s26, s34, s24
	s_addc_u32 s27, s35, s25
	s_add_u32 s24, s36, s24
	s_addc_u32 s25, s37, s25
	global_store_dword v67, v0, s[26:27]
	global_store_dword v67, v1, s[24:25]
